# class B second conversion pass takes items [2560,4096) from the HGRN workgroups (HGRN starts at 4608+g), on v_comb
# speedup vs baseline: 1.0085x; 1.0085x over previous
;     ...
;     { int it = (PART == 0 ? gw : I_IN + gw); const int end = (PART == 0 ? I_IN : (I_IN + it_last < NITEMS ? I_IN + it_last : NITEMS));
;       if (it < end) {
;         ConvItem pa = conv_item(a, ws, it), pb = pa; float wa[32], wb[32]; f32x4 ka[2], kb[2];
;         conv_load(pa, wa, ka, lane);
;         for (;;) {
;             const bool hb = it + NGW < end; if (hb) { pb = conv_item(a, ws, it + NGW); conv_load(pb, wb, kb, lane); }
.LBB0_416:
	s_mov_b64 s[2:3], -1
	s_and_b64 vcc, exec, s[0:1]
	s_cbranch_vccz .LBB0_511
	s_mov_b32 s99, 0
	s_movk_i32 s100, 0x2480
	s_movk_i32 s101, 0x207f
	s_lshl_b32 s0, s33, 3
	v_readlane_b32 s1, v254, 11
	s_add_i32 s0, s0, s1
	s_addk_i32 s0, 0xfe00

; __device__ __forceinline__ ConvItem conv_item(const Args& a, unsigned char* ws, int it) {
;     constexpr int I_IN = 16 * (INW / 32), I_SQ = 16 * 32, I_F1 = 16 * (2 * FFH / 32);
;     ConvItem p; int r = it; p.ks = nullptr; p.koff = 0; p.cs = 1.0f;
;     if (r < I_IN) { const int nblk = INW / 32, kb = r / nblk, nb = r % nblk, n0d = 32 * nb; const int sec = n0d >> 10; int n0s = n0d;
;         if (sec == 4 || sec == 5) { const int q = n0d & 255; n0s = (n0d - q) + 64 * ((q >> 5) & 3) + 32 * (q >> 7); }
;         p.W = a.in[2]; p.N = INW; p.WT = (bf16*)(ws + WS_WIN); p.ldT = 1024; p.k0 = 64 * kb; p.n0d = n0d; p.n0s = n0s; if (sec == 1 || sec == 3 || sec >= 7) p.cs = -1.4426950408889634f; return p; } r -= I_IN;
;     if (r < I_SQ) { p.W = a.in[7]; p.N = 1024; p.WT = (bf16*)(ws + WS_WHS); p.ldT = 2048; p.k0 = 64 * (r / 32); p.n0d = p.n0s = 32 * (r % 32); return p; } r -= I_SQ;
;     if (r < I_SQ) { p.W = a.in[8]; p.N = 1024; p.WT = (bf16*)(ws + WS_WHS); p.ldT = 2048; p.koff = 1024; p.k0 = 64 * (r / 32); p.n0d = p.n0s = 32 * (r % 32); return p; } r -= I_SQ;
;     if (r < I_SQ) { p.W = a.in[9]; p.N = 1024; p.WT = (bf16*)(ws + WS_WO); p.ldT = 1024; p.k0 = 64 * (r / 32); p.n0d = p.n0s = 32 * (r % 32); return p; } r -= I_SQ;
;     if (r < I_F1) { const int nblk = 2 * FFH / 32, kb = r / nblk, nb = r % nblk, n0d = 32 * nb, pn = n0d >> 8, q = n0d & 255;
;         p.W = a.in[11]; p.N = 2 * FFH; p.WT = (bf16*)(ws + WS_WF1); p.ldT = 1024; p.k0 = 64 * kb; p.n0d = n0d; p.n0s = (q >> 7) * FFH + 128 * pn + (q & 127); p.ks = a.in[10]; return p; } r -= I_F1;
;     p.W = a.in[12]; p.N = 1024; p.WT = (bf16*)(ws + WS_WF2); p.ldT = FFH; p.k0 = 64 * (r / 32); p.n0d = p.n0s = 32 * (r % 32); return p;
;     ...
;             const bool hb = it + NGW < end; if (hb) { pb = conv_item(a, ws, it + NGW); conv_load(pb, wb, kb, lane); }
;             conv_finish(pa, wa, ka, scr, lane);
;             if (!hb) break; it += NGW;
;             const bool ha = it + NGW < end; if (ha) { pa = conv_item(a, ws, it + NGW); conv_load(pa, wa, ka, lane); }
.LBB0_453:
	s_add_i32 s47, s40, 0x400
	s_cmp_lt_i32 s40, s100
	s_cselect_b64 s[2:3], -1, 0
	s_cmp_ge_i32 s40, s100
	s_cbranch_scc1 .LBB0_480
	s_cmpk_gt_i32 s40, 0xdff
	s_cbranch_scc0 .LBB0_460
	s_cmpk_gt_u32 s47, 0x13ff
	s_cbranch_scc0 .LBB0_461
	s_cmpk_gt_u32 s47, 0x15ff
	s_cbranch_scc0 .LBB0_462
	s_cmpk_gt_u32 s47, 0x17ff
	s_cbranch_scc0 .LBB0_463
	s_cmpk_gt_u32 s47, 0x22ff
	s_cbranch_scc0 .LBB0_464
	s_lshl_b32 s1, s47, 1
	s_add_i32 s1, s1, 0x7fffba00
	s_and_b32 s20, s1, 0x7fffffc0
	s_lshl_b32 s1, s47, 5
	s_and_b32 s30, s1, 0x3e0
	s_mov_b64 s[22:23], 0
	s_mov_b64 s[26:27], 0
	s_mov_b64 s[28:29], s[68:69]
	s_branch .LBB0_465

; #define LAS __attribute__((address_space(3)))
; __device__ __forceinline__ unsigned pk2(float lo, float hi) { return f2bf(lo) | (f2bf(hi) << 16); }
; __device__ __forceinline__ void conv_finish(const ConvItem& p, const float (&wv)[32], const f32x4 (&kv)[2], LAS float* scr, int lane) {
; #pragma unroll
;     for (int i = 0; i < 32; ++i) scr[(2 * i + (lane >> 5)) * 33 + (lane & 31)] = wv[i];
;     asm volatile("s_waitcnt lgkmcnt(0)" ::: "memory");
;     const int c = lane & 7;
; #pragma unroll
;     for (int j = 0; j < 4; ++j) { const int n = (lane >> 3) + 8 * j; const LAS float* s = scr + (8 * c) * 33 + n;
;         v4u o; o.x = pk2(s[0 * 33] * kv[0][0], s[1 * 33] * kv[0][1]); o.y = pk2(s[2 * 33] * kv[0][2], s[3 * 33] * kv[0][3]); o.z = pk2(s[4 * 33] * kv[1][0], s[5 * 33] * kv[1][1]); o.w = pk2(s[6 * 33] * kv[1][2], s[7 * 33] * kv[1][3]);
;         *(v4u*)(p.WT + (size_t)(p.n0d + n) * p.ldT + p.koff + p.k0 + 8 * c) = o; }
;     asm volatile("s_waitcnt lgkmcnt(0)" ::: "memory");
.LBB0_480:
	v_add_u32_e32 v96, 0x400, v63
	v_add_u32_e32 v97, 0x800, v63
	v_add_u32_e32 v98, 0xc00, v63
	v_add_u32_e32 v99, 0x1000, v63
	v_add_u32_e32 v100, 0x1400, v63
	v_add_u32_e32 v101, 0x1800, v63
	v_add_u32_e32 v102, 0x1c00, v63
	s_waitcnt vmcnt(30)
	ds_write2_b32 v63, v0, v1 offset1:66
	s_waitcnt vmcnt(28)
	ds_write2_b32 v63, v2, v3 offset0:132 offset1:198
	s_waitcnt vmcnt(26)
	ds_write2_b32 v96, v4, v5 offset0:8 offset1:74
	s_waitcnt vmcnt(24)
	ds_write2_b32 v96, v6, v7 offset0:140 offset1:206
	s_waitcnt vmcnt(22)
	ds_write2_b32 v97, v8, v9 offset0:16 offset1:82
	s_waitcnt vmcnt(20)
	ds_write2_b32 v97, v10, v11 offset0:148 offset1:214
	s_waitcnt vmcnt(18)
	ds_write2_b32 v98, v12, v13 offset0:24 offset1:90
	s_waitcnt vmcnt(16)
	ds_write2_b32 v98, v14, v15 offset0:156 offset1:222
	s_waitcnt vmcnt(14)
	ds_write2_b32 v99, v16, v17 offset0:32 offset1:98
	s_waitcnt vmcnt(12)
	ds_write2_b32 v99, v18, v19 offset0:164 offset1:230
	s_waitcnt vmcnt(10)
	ds_write2_b32 v100, v20, v21 offset0:40 offset1:106
	s_waitcnt vmcnt(8)
	ds_write2_b32 v100, v22, v23 offset0:172 offset1:238
	s_waitcnt vmcnt(6)
	ds_write2_b32 v101, v24, v25 offset0:48 offset1:114
	s_waitcnt vmcnt(4)
	ds_write2_b32 v101, v26, v27 offset0:180 offset1:246
	s_waitcnt vmcnt(2)
	ds_write2_b32 v102, v28, v29 offset0:56 offset1:122
	s_waitcnt vmcnt(0)
	ds_write2_b32 v102, v30, v31 offset0:188 offset1:254
	s_waitcnt lgkmcnt(0)
	ds_read2_b32 v[108:109], v58 offset0:33 offset1:41
	ds_read2_b32 v[110:111], v58 offset0:99 offset1:107
	ds_read2_b32 v[114:115], v58 offset0:165 offset1:173
	ds_read2_b32 v[116:117], v58 offset0:231 offset1:239
	v_mov_b32_e32 v54, v33
	v_mov_b32_e32 v55, v35
	s_waitcnt lgkmcnt(0)
	v_mov_b32_e32 v52, v108
	v_mov_b32_e32 v53, v110
	v_pk_mul_f32 v[52:53], v[54:55], v[52:53]
	ds_read2_b32 v[120:121], v58 offset0:132 offset1:140
	ds_read2_b32 v[122:123], v58 offset0:198 offset1:206
	v_bfe_u32 v103, v52, 16, 1
	v_add3_u32 v103, v52, v103, s44
	v_bfe_u32 v52, v53, 16, 1
	v_add3_u32 v104, v53, v52, s44
	v_mov_b32_e32 v112, v37
	v_mov_b32_e32 v113, v39
	v_mov_b32_e32 v52, v114
	v_mov_b32_e32 v53, v116
	v_pk_mul_f32 v[52:53], v[112:113], v[52:53]
	ds_read2_b32 v[126:127], v58 offset1:8
	ds_read2_b32 v[128:129], v58 offset0:66 offset1:74
	v_bfe_u32 v105, v52, 16, 1
	v_add3_u32 v105, v52, v105, s44
	v_bfe_u32 v52, v53, 16, 1
	v_add3_u32 v106, v53, v52, s44
	v_mov_b32_e32 v118, v36
	v_mov_b32_e32 v119, v38
	s_waitcnt lgkmcnt(3)
	v_mov_b32_e32 v52, v120
	s_waitcnt lgkmcnt(2)
	v_mov_b32_e32 v53, v122
	v_pk_mul_f32 v[52:53], v[118:119], v[52:53]
	v_mov_b32_e32 v124, v32
	v_bfe_u32 v107, v53, 16, 1
	v_add3_u32 v107, v53, v107, s44
	v_bfe_u32 v53, v52, 16, 1
	v_add3_u32 v108, v52, v53, s44
	v_mov_b32_e32 v125, v34
	s_waitcnt lgkmcnt(1)
	v_mov_b32_e32 v52, v126
	s_waitcnt lgkmcnt(0)
	v_mov_b32_e32 v53, v128
	v_pk_mul_f32 v[52:53], v[124:125], v[52:53]
	v_lshrrev_b32_e32 v108, 16, v108
	v_bfe_u32 v110, v53, 16, 1
	v_add3_u32 v53, v53, v110, s44
	v_bfe_u32 v110, v52, 16, 1
	v_add3_u32 v52, v52, v110, s44
	v_lshrrev_b32_e32 v107, 16, v107
	v_lshrrev_b32_e32 v53, 16, v53
	v_lshrrev_b32_e32 v52, 16, v52
	v_and_or_b32 v107, v106, s45, v107
	v_and_or_b32 v106, v105, s45, v108
	v_and_or_b32 v105, v104, s45, v53
	v_and_or_b32 v104, v103, s45, v52
	v_add_u32_e32 v52, s42, v57
	v_ashrrev_i32_e32 v103, 31, v52
	v_mad_u64_u32 v[52:53], s[26:27], s43, v52, 0
	v_mov_b32_e32 v108, v53
	v_mad_u64_u32 v[130:131], s[26:27], s43, v103, v[108:109]
	v_mov_b32_e32 v53, v130
	v_lshl_add_u64 v[52:53], v[52:53], 1, s[8:9]
	s_lshl_b64 s[26:27], s[6:7], 1
	s_ashr_i32 s5, s4, 31
	v_lshl_add_u64 v[52:53], v[52:53], 0, s[26:27]
	s_lshl_b64 s[28:29], s[4:5], 1
	v_lshl_add_u64 v[130:131], v[52:53], 0, s[28:29]
	v_lshlrev_b64 v[52:53], 1, v[50:51]
	v_lshl_add_u64 v[130:131], v[130:131], 0, v[52:53]
	v_mov_b32_e32 v110, v109
	global_store_dwordx4 v[130:131], v[104:107], off
	v_mov_b32_e32 v116, v115
	v_mov_b32_e32 v122, v121
	v_pk_mul_f32 v[104:105], v[54:55], v[110:111]
	v_mov_b32_e32 v128, v127
	v_bfe_u32 v103, v104, 16, 1
	v_add3_u32 v103, v104, v103, s44
	v_bfe_u32 v104, v105, 16, 1
	v_add3_u32 v108, v105, v104, s44
	v_pk_mul_f32 v[104:105], v[112:113], v[116:117]
	s_andn2_b64 vcc, exec, s[2:3]
	v_bfe_u32 v106, v104, 16, 1
	v_add3_u32 v106, v104, v106, s44
	v_bfe_u32 v104, v105, 16, 1
	v_add3_u32 v107, v105, v104, s44
	v_pk_mul_f32 v[104:105], v[118:119], v[122:123]
	s_nop 0
	v_bfe_u32 v109, v105, 16, 1
	v_add3_u32 v109, v105, v109, s44
	v_bfe_u32 v105, v104, 16, 1
	v_add3_u32 v110, v104, v105, s44
	v_pk_mul_f32 v[104:105], v[124:125], v[128:129]
	v_lshrrev_b32_e32 v109, 16, v109
	v_bfe_u32 v111, v105, 16, 1
	v_add3_u32 v105, v105, v111, s44
	v_bfe_u32 v111, v104, 16, 1
	v_add3_u32 v104, v104, v111, s44
	v_lshrrev_b32_e32 v104, 16, v104
	v_lshrrev_b32_e32 v105, 16, v105
	v_and_or_b32 v104, v103, s45, v104
	v_add_u32_e32 v103, s42, v59
	v_lshrrev_b32_e32 v110, 16, v110
	v_and_or_b32 v107, v107, s45, v109
	v_and_or_b32 v105, v108, s45, v105
	v_mad_u64_u32 v[108:109], s[30:31], s43, v103, 0
	v_and_or_b32 v106, v106, s45, v110
	v_ashrrev_i32_e32 v111, 31, v103
	v_mov_b32_e32 v110, v109
	v_mad_u64_u32 v[110:111], s[30:31], s43, v111, v[110:111]
	v_mov_b32_e32 v109, v110
	v_lshl_add_u64 v[108:109], v[108:109], 1, s[8:9]
	v_lshl_add_u64 v[108:109], v[108:109], 0, s[26:27]
	v_lshl_add_u64 v[108:109], v[108:109], 0, s[28:29]
	v_lshl_add_u64 v[108:109], v[108:109], 0, v[52:53]
	global_store_dwordx4 v[108:109], v[104:107], off
	ds_read2_b32 v[108:109], v58 offset0:49 offset1:57
	ds_read2_b32 v[110:111], v58 offset0:115 offset1:123
	ds_read2_b32 v[114:115], v58 offset0:181 offset1:189
	ds_read2_b32 v[116:117], v58 offset0:247 offset1:255
	ds_read2_b32 v[120:121], v58 offset0:148 offset1:156
	ds_read2_b32 v[122:123], v58 offset0:214 offset1:222
	ds_read2_b32 v[126:127], v58 offset0:16 offset1:24
	ds_read2_b32 v[128:129], v58 offset0:82 offset1:90
	s_waitcnt lgkmcnt(7)
; #define LAS __attribute__((address_space(3)))
; __device__ __forceinline__ unsigned pk2(float lo, float hi) { return f2bf(lo) | (f2bf(hi) << 16); }
; __device__ __forceinline__ void conv_finish(const ConvItem& p, const float (&wv)[32], const f32x4 (&kv)[2], LAS float* scr, int lane) {
;     ...
;     for (int j = 0; j < 4; ++j) { const int n = (lane >> 3) + 8 * j; const LAS float* s = scr + (8 * c) * 33 + n;
;         v4u o; o.x = pk2(s[0 * 33] * kv[0][0], s[1 * 33] * kv[0][1]); o.y = pk2(s[2 * 33] * kv[0][2], s[3 * 33] * kv[0][3]); o.z = pk2(s[4 * 33] * kv[1][0], s[5 * 33] * kv[1][1]); o.w = pk2(s[6 * 33] * kv[1][2], s[7 * 33] * kv[1][3]);
;         *(v4u*)(p.WT + (size_t)(p.n0d + n) * p.ldT + p.koff + p.k0 + 8 * c) = o; }
;     ...
;     { int it = (PART == 0 ? gw : I_IN + gw); const int end = (PART == 0 ? I_IN : (I_IN + it_last < NITEMS ? I_IN + it_last : NITEMS));
;       if (it < end) {
;         ConvItem pa = conv_item(a, ws, it), pb = pa; float wa[32], wb[32]; f32x4 ka[2], kb[2];
;         conv_load(pa, wa, ka, lane);
;         for (;;) {
;             const bool hb = it + NGW < end; if (hb) { pb = conv_item(a, ws, it + NGW); conv_load(pb, wb, kb, lane); }
;             conv_finish(pa, wa, ka, scr, lane);
;             if (!hb) break; it += NGW;
;             const bool ha = it + NGW < end; if (ha) { pa = conv_item(a, ws, it + NGW); conv_load(pa, wa, ka, lane); }
;             conv_finish(pb, wb, kb, scr, lane);
;             if (!ha) break; it += NGW;
	v_mov_b32_e32 v104, v108
	s_waitcnt lgkmcnt(6)
	v_mov_b32_e32 v105, v110
	v_pk_mul_f32 v[104:105], v[54:55], v[104:105]
	s_nop 0
	v_bfe_u32 v103, v104, 16, 1
	v_add3_u32 v103, v104, v103, s44
	v_bfe_u32 v104, v105, 16, 1
	v_add3_u32 v108, v105, v104, s44
	s_waitcnt lgkmcnt(5)
	v_mov_b32_e32 v104, v114
	s_waitcnt lgkmcnt(4)
	v_mov_b32_e32 v105, v116
	v_pk_mul_f32 v[104:105], v[112:113], v[104:105]
	s_nop 0
	v_bfe_u32 v106, v104, 16, 1
	v_add3_u32 v106, v104, v106, s44
	v_bfe_u32 v104, v105, 16, 1
	v_add3_u32 v107, v105, v104, s44
	s_waitcnt lgkmcnt(3)
	v_mov_b32_e32 v104, v120
	s_waitcnt lgkmcnt(2)
	v_mov_b32_e32 v105, v122
	v_pk_mul_f32 v[104:105], v[118:119], v[104:105]
	v_mov_b32_e32 v122, v121
	v_bfe_u32 v110, v105, 16, 1
	v_add3_u32 v110, v105, v110, s44
	v_bfe_u32 v105, v104, 16, 1
	v_add3_u32 v114, v104, v105, s44
	s_waitcnt lgkmcnt(1)
	v_mov_b32_e32 v104, v126
	s_waitcnt lgkmcnt(0)
	v_mov_b32_e32 v105, v128
	v_pk_mul_f32 v[104:105], v[124:125], v[104:105]
	v_lshrrev_b32_e32 v110, 16, v110
	v_bfe_u32 v116, v105, 16, 1
	v_add3_u32 v105, v105, v116, s44
	v_bfe_u32 v116, v104, 16, 1
	v_add3_u32 v104, v104, v116, s44
	v_lshrrev_b32_e32 v104, 16, v104
	v_and_or_b32 v104, v103, s45, v104
	v_add_u32_e32 v103, s42, v60
	v_lshrrev_b32_e32 v105, 16, v105
	v_mad_u64_u32 v[130:131], s[30:31], s43, v103, 0
	v_and_or_b32 v107, v107, s45, v110
	v_and_or_b32 v105, v108, s45, v105
	v_ashrrev_i32_e32 v110, 31, v103
	v_mov_b32_e32 v108, v131
	v_mad_u64_u32 v[132:133], s[30:31], s43, v110, v[108:109]
	v_mov_b32_e32 v131, v132
	v_mov_b32_e32 v110, v109
	v_lshl_add_u64 v[130:131], v[130:131], 1, s[8:9]
	v_pk_mul_f32 v[54:55], v[54:55], v[110:111]
	v_lshl_add_u64 v[130:131], v[130:131], 0, s[26:27]
	v_mov_b32_e32 v116, v115
	v_bfe_u32 v103, v54, 16, 1
	v_lshrrev_b32_e32 v114, 16, v114
	v_lshl_add_u64 v[130:131], v[130:131], 0, s[28:29]
	v_pk_mul_f32 v[108:109], v[112:113], v[116:117]
	v_add3_u32 v54, v54, v103, s44
	v_bfe_u32 v103, v55, 16, 1
	v_and_or_b32 v106, v106, s45, v114
	v_lshl_add_u64 v[130:131], v[130:131], 0, v[52:53]
	v_add3_u32 v55, v55, v103, s44
	v_bfe_u32 v103, v108, 16, 1
	global_store_dwordx4 v[130:131], v[104:107], off
	v_add3_u32 v103, v108, v103, s44
	v_bfe_u32 v108, v109, 16, 1
	v_pk_mul_f32 v[106:107], v[118:119], v[122:123]
	v_mov_b32_e32 v128, v127
	v_add3_u32 v108, v109, v108, s44
	v_bfe_u32 v109, v107, 16, 1
	v_pk_mul_f32 v[104:105], v[124:125], v[128:129]
	v_add3_u32 v107, v107, v109, s44
	v_bfe_u32 v109, v106, 16, 1
	v_add3_u32 v106, v106, v109, s44
	v_bfe_u32 v109, v105, 16, 1
	v_add3_u32 v105, v105, v109, s44
	v_bfe_u32 v109, v104, 16, 1
	v_lshrrev_b32_e32 v106, 16, v106
	v_add3_u32 v104, v104, v109, s44
	v_and_or_b32 v106, v103, s45, v106
	v_lshrrev_b32_e32 v103, 16, v105
	v_and_or_b32 v105, v55, s45, v103
	v_lshrrev_b32_e32 v55, 16, v104
	v_and_or_b32 v104, v54, s45, v55
	v_add_u32_e32 v54, s42, v61
	v_lshrrev_b32_e32 v107, 16, v107
	v_ashrrev_i32_e32 v103, 31, v54
	v_mad_u64_u32 v[54:55], s[30:31], s43, v54, 0
	v_and_or_b32 v107, v108, s45, v107
	v_mov_b32_e32 v108, v55
	v_mad_u64_u32 v[108:109], s[30:31], s43, v103, v[108:109]
	v_mov_b32_e32 v55, v108
	v_lshl_add_u64 v[54:55], v[54:55], 1, s[8:9]
	v_lshl_add_u64 v[54:55], v[54:55], 0, s[26:27]
	v_lshl_add_u64 v[54:55], v[54:55], 0, s[28:29]
	v_lshl_add_u64 v[54:55], v[54:55], 0, v[52:53]
	global_store_dwordx4 v[54:55], v[104:107], off
	s_waitcnt lgkmcnt(0)
	s_mov_b64 s[26:27], -1
	s_cbranch_vccnz .LBB0_452
	s_cmp_gt_i32 s40, s101
	s_cselect_b64 s[26:27], -1, 0
	s_and_b64 vcc, exec, s[26:27]
	s_cbranch_vccnz .LBB0_451
	s_add_i32 s47, s40, 0x800
	s_cmpk_gt_i32 s40, 0x9ff
	s_cbranch_scc0 .LBB0_489
	s_cmpk_gt_u32 s47, 0x13ff
	s_cbranch_scc0 .LBB0_490
	s_cmpk_gt_u32 s47, 0x15ff
	s_cbranch_scc0 .LBB0_491
	s_cmpk_gt_u32 s47, 0x17ff
	s_cbranch_scc0 .LBB0_492
	s_cmpk_gt_u32 s47, 0x22ff
	s_cbranch_scc0 .LBB0_493
	s_lshl_b32 s1, s47, 1
	s_add_i32 s1, s1, 0x7fffba00
	s_and_b32 s4, s1, 0x7fffffc0
	s_lshl_b32 s1, s47, 5
	s_and_b32 s34, s1, 0x3e0
	s_mov_b64 s[2:3], 0
	s_mov_b64 s[28:29], 0
	s_mov_b64 s[30:31], s[68:69]
	s_branch .LBB0_494

;     ...
;     { int it = (PART == 0 ? gw : I_IN + gw); const int end = (PART == 0 ? I_IN : (I_IN + it_last < NITEMS ? I_IN + it_last : NITEMS));
;       if (it < end) {
;         ConvItem pa = conv_item(a, ws, it), pb = pa; float wa[32], wb[32]; f32x4 ka[2], kb[2];
;         conv_load(pa, wa, ka, lane);
;         for (;;) {
;             const bool hb = it + NGW < end; if (hb) { pb = conv_item(a, ws, it + NGW); conv_load(pb, wb, kb, lane); }
; __global__ void __launch_bounds__(NTHREADS, 2) hybrid_fwd(Args args) {
;     ...
;                 if (idx < 128) p0_prologue<1>(args, lds, wave, lane, idx * NWAVES + wave, 1024, 2048);
;                 else p0_prologue<1>(args, lds, wave, lane, 2048 + (idx - 128) * NWAVES + wave, 1024);
.LBB0_510:
	s_cmp_lg_u32 s99, 0
	s_cbranch_scc1 .Lmy_cv_done
	s_mov_b32 s99, 1
	s_movk_i32 s100, 0x1e00
	s_movk_i32 s101, 0x19ff
	s_lshl_b32 s0, s33, 3
	v_readlane_b32 s1, v254, 11
	s_add_i32 s0, s0, s1
	s_addk_i32 s0, 0x400
	s_branch .Lmy_cv2

;     ...
;     { int it = (PART == 0 ? gw : I_IN + gw); const int end = (PART == 0 ? I_IN : (I_IN + it_last < NITEMS ? I_IN + it_last : NITEMS));
;       if (it < end) {
;         ConvItem pa = conv_item(a, ws, it), pb = pa; float wa[32], wb[32]; f32x4 ka[2], kb[2];
;         conv_load(pa, wa, ka, lane);
;         for (;;) {
;             const bool hb = it + NGW < end; if (hb) { pb = conv_item(a, ws, it + NGW); conv_load(pb, wb, kb, lane); }
; __global__ void __launch_bounds__(NTHREADS, 2) hybrid_fwd(Args args) {
;     ...
;             if ((int)blockIdx.x < 64) { hgrn_v2(args, lds, (int)blockIdx.x, 64); p0_prologue<1>(args, lds, wave, lane, 2048 + 512 + (int)blockIdx.x * NWAVES + wave, 1024); S.l0 = -1; S.l1 = -1; S.l2 = -1; }
;             else { const int idx = (int)blockIdx.x - 64;
;                 if (idx < 128) attn_mfma(args, idx * 40 + wave, 5, NWAVES); else attn_mfma(args, 5120 + (idx - 128) * 48 + wave, 6, NWAVES);
;                 if (idx < 128) p0_prologue<1>(args, lds, wave, lane, idx * NWAVES + wave, 1024, 2048);
;                 else p0_prologue<1>(args, lds, wave, lane, 2048 + (idx - 128) * NWAVES + wave, 1024);
.LBB0_580:
	s_lshl_b32 s0, s33, 3
	v_readlane_b32 s1, v254, 11
	s_add_i32 s0, s0, s1
	s_addk_i32 s0, 0x1200
	s_cmpk_gt_i32 s0, 0x167f
	s_cbranch_scc1 .LBB0_666
	s_add_i32 s38, s0, 0x1200
	s_cmp_gt_i32 s0, -1
	s_cbranch_scc0 .LBB0_587
	s_cmpk_gt_u32 s38, 0x13ff
	s_cbranch_scc0 .LBB0_588
	s_cmpk_gt_u32 s38, 0x15ff
	s_cbranch_scc0 .LBB0_589
	s_cmpk_gt_u32 s38, 0x17ff
	s_cbranch_scc0 .LBB0_590
	s_cmpk_gt_u32 s38, 0x22ff
	s_cbranch_scc0 .LBB0_591
	s_add_u32 s8, s72, 0x2500000
	s_addc_u32 s9, s73, 0
	s_lshl_b32 s0, s38, 1
	s_add_i32 s0, s0, 0x7fffba00
	s_and_b32 s4, s0, 0x7fffffc0
	s_lshl_b32 s0, s38, 5
	s_and_b32 s10, s0, 0x3e0
	s_mov_b64 s[6:7], 0
	s_mov_b64 s[0:1], 0
	s_mov_b64 s[2:3], s[68:69]
	s_branch .LBB0_592
